# DIFF attention: near-diagonal tiles take T5 bias and causal mask from one extended LDS table (one ds_read2 per two scores) in a hand-scheduled body
# baseline (speedup 1.0000x reference)
; template <int MODE>
; __device__ __forceinline__ void attn_item(const Params& P, int layer, int b, int h, int map, int qb) {
;     ...
;   if (MODE != 0) { if (tid < 129) tab[tid] = P.rel_bias[T5B[tid] * 10 + bcol] * LOG2E; }
;   bf16x8 qf[NST];
; #pragma unroll
;   for (int s = 0; s < NST; ++s) qf[s] = qvalid ? *(const bf16x8*)(qp + (size_t)e_q * KLD + s * 16 + hh * 8) : (bf16x8){0, 0, 0, 0, 0, 0, 0, 0};
;   int tstart = 1, ntl;
;   if (meta) ntl = 1; else if (MODE == 2) { tstart = max(1, 4 * qb - 1); ntl = 4 * qb + 6 - tstart; } else ntl = 4 * qb + 5;
;   SM sa;
;   sa.m = NEG; sa.l = 0.f;
; #pragma unroll
;   for (int i = 0; i < 16; ++i) { sa.o0[i] = 0.f; sa.o1[i] = 0.f; }
;   if (MODE == 2) { sa.m = P.sinks[layer * 6 + h] * LOG2E; sa.l = hh == 0 ? 1.f : 0.f; }
;   float cfar = 0.f; if (MODE == 1) cfar = P.rel_bias[31 * 10 + bcol] * LOG2E;
;   struct Stage { u32x4 k[NLK], v; };
;   Stage stX, stY;
;   auto issue = [&](Stage& st, int t) {
; #pragma unroll
;     for (int u = 0; u < NLK; ++u) { int c = tid + 512 * u; if (c >= NKC) c -= (NKC % 512 == 0 ? 512 : NKC % 512);
;       const int row = c / CPR, cc = c % CPR; st.k[u] = *(const u32x4*)(kp + (size_t)(64 * t + row) * KLD + cc * 8); }
;     { const int row = tid >> 3, cc = tid & 7; st.v = *(const u32x4*)(vp + (size_t)row * E + 64 * t + cc * 8); }
;   };
;   auto commit = [&](const Stage& st, int bufi) {
; #pragma unroll
;     for (int u = 0; u < NLK; ++u) { int c = tid + 512 * u; if (c >= NKC) c -= (NKC % 512 == 0 ? 512 : NKC % 512);
;       const int row = c / CPR, cc = c % CPR; *(LAS u32x4*)(lds + bufi * KBUF + row * KSTR + cc * 16) = st.k[u]; }
;     { const int row = tid >> 3, cc = tid & 7; *(LAS u32x4*)(lds + 4 * KBUF + bufi * VBUF + row * 144 + cc * 16) = st.v; }
;   };
;   auto tile_of = [&](int i) { return i == 0 ? 0 : tstart + i - 1; };
;   auto skipf = [&](int t) { bool sk = !active; if (t > 0) { if (64 * t > eq0 + 31) sk = true; if (MODE == 2 && eq0 - (64 * t + 63) >= 128) sk = true; } return sk; };
;   const int pr = (r & 0x13) | ((r & 4) << 1) | ((r & 8) >> 1);
;   auto lookf = [&](int t) { return MODE != 0 && (t == 0 || MODE == 2 || (eq0 - (64 * t + 63) < 128)); };
;   auto qk = [&](f32x16& s0, f32x16& s1, float& boff, int bufi, int t) {
;     const ldsp_t kbuf = lds + bufi * KBUF;
;     __builtin_amdgcn_s_setprio(1);
;     boff = sa.m > -1e29f ? sa.m : 0.f;
.LBB0_1247:
	s_or_b64 exec, exec, s[2:3]
	v_cmp_lt_i32_e32 vcc, 63, v166
	v_subrev_u32_e32 v4, 48, v166
	v_lshlrev_b32_e32 v168, 3, v6
	v_cndmask_b32_e32 v169, v166, v4, vcc
	global_load_dword v4, v1, s[38:39] offset:1240
	v_lshlrev_b32_e32 v5, 1, v2
	v_lshrrev_b32_e32 v6, 1, v2
	v_and_b32_e32 v5, 8, v5
	v_and_b32_e32 v6, 4, v6
	v_cmp_lt_i32_e32 vcc, s92, v2
	s_lshl_b32 s2, s37, 1
	s_add_u32 s2, s61, s2
	s_addc_u32 s3, s58, 0
	v_and_b32_e32 v167, 63, v2
	v_ashrrev_i32_e32 v28, 3, v2
	v_mov_b64_e32 v[8:9], s[34:35]
	s_or_b64 s[68:69], s[72:73], s[4:5]
	v_mad_i64_i32 v[22:23], s[4:5], v28, s95, v[8:9]
	v_mov_b32_e32 v25, v1
	s_lshl_b32 s90, s76, 1
	v_lshl_add_u64 v[16:17], v[22:23], 0, s[90:91]
	s_lshl_b32 s90, s77, 1
	v_mul_u32_u24_e32 v224, 0x90, v3
	v_mov_b32_e32 v3, v1
	v_mov_b32_e32 v223, 0xf149f2ca
	s_xor_b64 s[40:41], s[68:69], -1
	s_or_b32 s37, s36, 31
	s_sub_i32 s80, s36, 63
	v_add_u32_e32 v225, 48, v169
	v_add_u32_e32 v226, s51, v169
	s_mov_b32 s48, 0
	v_mov_b32_e32 v177, 0xf149f2ca
	v_mov_b32_e32 v228, 0
	s_waitcnt vmcnt(0)
	v_mul_f32_e32 v221, 0x3fb8aa3b, v4
	v_and_b32_e32 v4, 19, v2
	v_or3_b32 v26, v4, v5, v6
	v_add_u32_e32 v4, 0xffffff00, v2
	v_cndmask_b32_e32 v4, v2, v4, vcc
	v_ashrrev_i32_e32 v5, 31, v4
	v_lshrrev_b32_e32 v5, 30, v5
	v_add_u32_e32 v5, v4, v5
	v_ashrrev_i32_e32 v170, 2, v5
	v_and_b32_e32 v5, -4, v5
	v_sub_u32_e32 v27, v4, v5
	v_ashrrev_i32_e32 v171, 31, v170
	v_lshlrev_b32_e32 v6, 3, v27
	v_lshlrev_b64 v[4:5], 7, v[170:171]
	v_ashrrev_i32_e32 v7, 31, v6
	v_lshl_add_u64 v[4:5], s[2:3], 0, v[4:5]
	v_lshlrev_b64 v[20:21], 1, v[6:7]
	v_lshl_add_u64 v[4:5], v[4:5], 0, v[20:21]
	global_load_dwordx4 v[4:7], v[4:5], off
	v_add_u32_e32 v12, s76, v170
	v_lshlrev_b32_e32 v2, 4, v2
	v_ashrrev_i32_e32 v13, 31, v12
	v_and_b32_e32 v24, 0x70, v2
	v_lshlrev_b64 v[12:13], 7, v[12:13]
	v_lshl_add_u64 v[172:173], v[22:23], 0, v[24:25]
	v_lshl_add_u64 v[12:13], s[2:3], 0, v[12:13]
	global_load_dwordx4 v[8:11], v[172:173], off
	v_lshl_add_u64 v[12:13], v[12:13], 0, v[20:21]
	global_load_dwordx4 v[12:15], v[12:13], off
	v_lshl_add_u64 v[16:17], v[16:17], 0, v[24:25]
	global_load_dwordx4 v[16:19], v[16:17], off
	v_mul_lo_u32 v2, v170, s86
	v_lshlrev_b32_e32 v27, 4, v27
	v_add3_u32 v171, 0, v2, v27
	v_mul_lo_u32 v2, v28, s54
	v_add3_u32 v222, 0, v2, v24
	v_mul_u32_u24_e32 v2, 0x50, v26
	v_lshl_add_u64 v[174:175], s[2:3], 0, v[20:21]
	v_add3_u32 v227, 0, v2, v0
	v_mov_b32_e32 v2, v1
	s_waitcnt vmcnt(3)
	ds_write_b128 v171, v[4:7]
	v_add_u32_e32 v4, s77, v170
	v_ashrrev_i32_e32 v5, 31, v4
	v_lshlrev_b64 v[4:5], 7, v[4:5]
	v_lshl_add_u64 v[4:5], s[2:3], 0, v[4:5]
	s_waitcnt vmcnt(2)
	ds_write_b128 v222, v[8:11] offset:20480
	s_waitcnt vmcnt(1)
	ds_write_b128 v171, v[12:15] offset:5120
	s_waitcnt vmcnt(0)
	ds_write_b128 v222, v[16:19] offset:29696
	v_lshl_add_u64 v[4:5], v[4:5], 0, v[20:21]
	global_load_dwordx4 v[106:109], v[4:5], off
	v_lshl_add_u64 v[4:5], v[22:23], 0, s[90:91]
	v_lshl_add_u64 v[4:5], v[4:5], 0, v[24:25]
	global_load_dwordx4 v[110:113], v[4:5], off
	v_add_u32_e32 v4, s50, v170
	v_ashrrev_i32_e32 v5, 31, v4
	v_lshlrev_b64 v[4:5], 7, v[4:5]
	v_lshl_add_u64 v[4:5], s[2:3], 0, v[4:5]
	v_lshl_add_u64 v[4:5], v[4:5], 0, v[20:21]
	s_lshl_b32 s90, s50, 1
	global_load_dwordx4 v[114:117], v[4:5], off
	v_lshl_add_u64 v[4:5], v[22:23], 0, s[90:91]
	v_lshl_add_u64 v[4:5], v[4:5], 0, v[24:25]
	global_load_dwordx4 v[118:121], v[4:5], off
	v_mov_b32_e32 v16, v1
	v_mov_b32_e32 v17, v1
	v_mov_b32_e32 v4, v1
	v_mov_b32_e32 v5, v1
	v_mov_b32_e32 v6, v1
	v_mov_b32_e32 v7, v1
	v_mov_b32_e32 v8, v1
	v_mov_b32_e32 v9, v1
	v_mov_b32_e32 v10, v1
	v_mov_b32_e32 v11, v1
	v_mov_b32_e32 v12, v1
	v_mov_b32_e32 v13, v1
	v_mov_b32_e32 v14, v1
	v_mov_b32_e32 v15, v1
	v_mov_b64_e32 v[32:33], v[16:17]
	v_mov_b64_e32 v[30:31], v[14:15]
	v_mov_b64_e32 v[28:29], v[12:13]
	v_mov_b64_e32 v[26:27], v[10:11]
	v_mov_b64_e32 v[24:25], v[8:9]
	v_mov_b64_e32 v[22:23], v[6:7]
	v_mov_b64_e32 v[20:21], v[4:5]
	v_mov_b64_e32 v[18:19], v[2:3]
	s_waitcnt lgkmcnt(0)
	s_barrier
	v_subrev_u32_e32 v34, 96, v155
	v_max_i32_e32 v34, 0, v34
	v_min_i32_e32 v34, 0x80, v34
	v_lshlrev_b32_e32 v34, 2, v34
	ds_read_b32 v35, v34 offset:57344
	v_mov_b32_e32 v36, 0xf149f2ca
	v_cmp_gt_u32_e32 vcc, 96, v155
	s_waitcnt lgkmcnt(0)
	v_cndmask_b32_e32 v35, v35, v36, vcc
	v_lshlrev_b32_e32 v34, 2, v155
	v_add_u32_e32 v34, 0x1e400, v34
	v_cmp_gt_u32_e32 vcc, 0x180, v155
	s_and_saveexec_b64 s[2:3], vcc
	ds_write_b32 v34, v35
	s_or_b64 exec, exec, s[2:3]
	s_waitcnt lgkmcnt(0)
	s_barrier
	s_branch .LBB0_1251

.LBB0_1251:
	s_and_b32 s78, s48, 2
	s_cmp_lt_u32 s48, 2
	s_cbranch_scc1 .Ldf_gen
	s_lshl_b32 s2, s48, 6
	s_sub_i32 s2, s80, s2
	s_cmpk_gt_i32 s2, 0xbf
	s_cbranch_scc1 .Ldf_fast
	s_lshl_b32 s3, s48, 6
	s_addk_i32 s3, 0x40
	s_cmp_le_i32 s3, s37
	s_cbranch_scc1 .Ldn_near

; #define LAS __attribute__((address_space(3)))
; __device__ __forceinline__ float max3f(float a, float b, float c) { return __builtin_fmaxf(__builtin_fmaxf(a, b), c); }
; __device__ __forceinline__ void softmax_tile(f32x16& s0, f32x16& s1, SM& st, float boff, ldsp_t vb, int hh, int r) {
;     ...
;   float zmax = max3f(s0[0], s0[1], s0[2]);
; #pragma unroll
;   for (int k = 0; k < 6; ++k) zmax = max3f(zmax, s0[3 + 2 * k], s0[4 + 2 * k]);
;   zmax = max3f(zmax, s0[15], s1[0]);
; #pragma unroll
;   for (int k = 0; k < 7; ++k) zmax = max3f(zmax, s1[1 + 2 * k], s1[2 + 2 * k]);
;   zmax = fmaxf(zmax, s1[15]);
; #pragma unroll
;   for (int i = 0; i < 16; ++i) { s0[i] = __builtin_amdgcn_exp2f(s0[i]); s1[i] = __builtin_amdgcn_exp2f(s1[i]); }
;   if (__any((zmax + boff > st.m + DEFER_THR) || (st.m != boff))) {
; template <int MODE>
; __device__ __forceinline__ void attn_item(const Params& P, int layer, int b, int h, int map, int qb) {
;     ...
;       const bf16x8 a0 = *(LAS const bf16x8*)(kbuf + pr * KSTR + s * 32 + hh * 16);
;       const bf16x8 a1 = *(LAS const bf16x8*)(kbuf + (32 + pr) * KSTR + s * 32 + hh * 16);
;       s0 = __builtin_amdgcn_mfma_f32_32x32x16_bf16(a0, qf[s], s0, 0, 0, 0);
;       s1 = __builtin_amdgcn_mfma_f32_32x32x16_bf16(a1, qf[s], s1, 0, 0, 0);
.Ldf_noinit:
	v_add3_u32 v158, s6, v224, v0
	v_add3_u32 v246, s7, v224, v0
	s_waitcnt lgkmcnt(7)
	v_mfma_f32_32x32x16_bf16 v[50:65], v[178:181], v[102:105], v[230:245]
	s_waitcnt lgkmcnt(6)
	v_mfma_f32_32x32x16_bf16 v[34:49], v[182:185], v[102:105], v[230:245]
	s_waitcnt lgkmcnt(5)
	v_mfma_f32_32x32x16_bf16 v[50:65], v[186:189], v[98:101], v[50:65]
	s_waitcnt lgkmcnt(4)
	v_mfma_f32_32x32x16_bf16 v[34:49], v[190:193], v[98:101], v[34:49]
	ds_read_b128 v[146:149], v158 offset:20480
	ds_read_b128 v[142:145], v158 offset:20512
	ds_read_b128 v[150:153], v158 offset:25088
	ds_read_b128 v[138:141], v158 offset:25120
	ds_read_b128 v[134:137], v158 offset:20544
	ds_read_b128 v[126:129], v158 offset:20576
	ds_read_b128 v[130:133], v158 offset:25152
	ds_read_b128 v[122:125], v158 offset:25184
	s_waitcnt lgkmcnt(11)
	v_mfma_f32_32x32x16_bf16 v[82:97], v[194:197], v[102:105], v[230:245]
	s_waitcnt lgkmcnt(10)
	v_mfma_f32_32x32x16_bf16 v[66:81], v[198:201], v[102:105], v[230:245]
	v_max3_f32 v156, v50, v51, v52
	v_max3_f32 v156, v156, v53, v54
	v_max3_f32 v156, v156, v55, v56
	v_max3_f32 v156, v156, v57, v58
	v_max3_f32 v156, v156, v59, v60
	v_max3_f32 v156, v156, v61, v62
	v_max3_f32 v156, v156, v63, v64
	v_max3_f32 v156, v156, v65, v34
	v_max3_f32 v156, v156, v35, v36
	v_max3_f32 v156, v156, v37, v38
	v_max3_f32 v156, v156, v39, v40
	v_max3_f32 v156, v156, v41, v42
	v_max3_f32 v156, v156, v43, v44
	v_max3_f32 v156, v156, v45, v46
	v_max3_f32 v156, v156, v47, v48
	v_max_f32_e32 v156, v156, v49
	v_exp_f32_e32 v50, v50
	v_exp_f32_e32 v34, v34
	s_waitcnt lgkmcnt(9)
	v_mfma_f32_32x32x16_bf16 v[82:97], v[202:205], v[98:101], v[82:97]
	v_exp_f32_e32 v51, v51
	v_exp_f32_e32 v35, v35
	v_exp_f32_e32 v52, v52
	v_exp_f32_e32 v36, v36
	v_exp_f32_e32 v53, v53
	v_exp_f32_e32 v37, v37
	v_exp_f32_e32 v54, v54
	v_exp_f32_e32 v38, v38
	v_exp_f32_e32 v55, v55
	v_exp_f32_e32 v39, v39
	v_exp_f32_e32 v56, v56
	v_exp_f32_e32 v40, v40
	v_exp_f32_e32 v57, v57
	v_exp_f32_e32 v41, v41
	v_exp_f32_e32 v58, v58
	v_exp_f32_e32 v42, v42
	v_exp_f32_e32 v59, v59
	v_exp_f32_e32 v43, v43
	v_exp_f32_e32 v60, v60
	v_exp_f32_e32 v44, v44
	s_waitcnt lgkmcnt(8)
	v_mfma_f32_32x32x16_bf16 v[66:81], v[206:209], v[98:101], v[66:81]
	v_exp_f32_e32 v61, v61
	v_exp_f32_e32 v45, v45
	v_exp_f32_e32 v62, v62
	v_exp_f32_e32 v46, v46
	v_exp_f32_e32 v63, v63
	v_exp_f32_e32 v47, v47
	v_exp_f32_e32 v64, v64
	v_exp_f32_e32 v48, v48
	v_exp_f32_e32 v65, v65
	v_exp_f32_e32 v49, v49
	v_add_f32_e32 v160, v176, v156
	v_add_f32_e32 v161, v177, v157
	v_cmp_neq_f32_e64 s[4:5], v177, v176
	v_cmp_gt_f32_e32 vcc, v160, v161
	s_or_b64 vcc, s[4:5], vcc
	s_cbranch_vccnz .Ldf_slow_a

; __device__ __forceinline__ float max3f(float a, float b, float c) { return __builtin_fmaxf(__builtin_fmaxf(a, b), c); }
; __device__ __forceinline__ void softmax_tile(f32x16& s0, f32x16& s1, SM& st, float boff, ldsp_t vb, int hh, int r) {
;     ...
;   float zmax = max3f(s0[0], s0[1], s0[2]);
; #pragma unroll
;   for (int k = 0; k < 6; ++k) zmax = max3f(zmax, s0[3 + 2 * k], s0[4 + 2 * k]);
;   zmax = max3f(zmax, s0[15], s1[0]);
; #pragma unroll
;   for (int k = 0; k < 7; ++k) zmax = max3f(zmax, s1[1 + 2 * k], s1[2 + 2 * k]);
;   zmax = fmaxf(zmax, s1[15]);
; #pragma unroll
;   for (int i = 0; i < 16; ++i) { s0[i] = __builtin_amdgcn_exp2f(s0[i]); s1[i] = __builtin_amdgcn_exp2f(s1[i]); }
;   if (__any((zmax + boff > st.m + DEFER_THR) || (st.m != boff))) {
; template <int MODE, bool lookup, int MK>
; __device__ __forceinline__ void softmax_pv(f32x16& s0, f32x16& s1, SM& st, float boff, ldsp_t vb, LAS const float* tab, int t, int e_q, int posq, int hh, int r, bool mask_rt, float negv) {
;     ...
;   const int ekb = 64 * t + 8 * hh, koff = t == 0 ? 0 : 48, klim = t == 0 ? 16 : 0x7fffffff;
;   if (MODE != 0) {
;     if (lookup) {
; #pragma unroll
;       for (int i = 0; i < 16; ++i) { const int ek = ekb + (i & 7) + 16 * (i >> 3); int n0 = posq - (ek - koff), n1 = n0 - 32; n0 = (int)min((unsigned)n0, 128u); n1 = (int)min((unsigned)n1, 128u); s0[i] += tab[n0]; s1[i] += tab[n1]; }
;     }
;   }
;   if (need_mask) {
; #pragma unroll
;     for (int i = 0; i < 16; ++i) { const int ek0 = ekb + (i & 7) + 16 * (i >> 3), ek1 = ek0 + 32;
;       const bool v0 = (ek0 <= e_q) && (ek0 < klim) && (MODE != 2 || t == 0 || (e_q - ek0 < 128));
;       const bool v1 = (ek1 <= e_q) && (ek1 < klim) && (MODE != 2 || t == 0 || (e_q - ek1 < 128));
;       s0[i] = v0 ? s0[i] : negv; s1[i] = v1 ? s1[i] : negv; }
;   }
;   softmax_tile(s0, s1, st, boff, vb, hh, r);
.Ldn_near:
	s_mul_i32 s6, s78, 0x1400
	s_or_b32 s7, s78, 1
	s_mul_i32 s2, s7, 0x1400
	s_mul_i32 s3, s78, 0x2400
	s_mul_i32 s7, s7, 0x2400
	v_cmp_lt_f32_e32 vcc, s87, v177
	s_lshl_b32 s84, s48, 8
	s_nop 0
	v_cndmask_b32_e32 v176, 0, v177, vcc
	v_sub_f32_e32 v230, 0, v176
	v_mov_b32_e32 v231, v230
	v_mov_b32_e32 v232, v230
	v_mov_b32_e32 v233, v230
	v_mov_b32_e32 v234, v230
	v_mov_b32_e32 v235, v230
	v_mov_b32_e32 v236, v230
	v_mov_b32_e32 v237, v230
	v_mov_b32_e32 v238, v230
	v_mov_b32_e32 v239, v230
	v_mov_b32_e32 v240, v230
	v_mov_b32_e32 v241, v230
	v_mov_b32_e32 v242, v230
	v_mov_b32_e32 v243, v230
	v_mov_b32_e32 v244, v230
	v_mov_b32_e32 v245, v230
	v_mov_b32_e32 v252, 0x7fc00000
	v_sub_u32_e32 v248, v166, v168
	v_lshlrev_b32_e32 v248, 2, v248
	v_add_u32_e32 v248, 0x1e484, v248
	v_add_u32_e32 v160, s6, v227
	ds_read_b128 v[178:181], v160
	ds_read_b128 v[182:185], v160 offset:2560
	ds_read_b128 v[186:189], v160 offset:32
	ds_read_b128 v[190:193], v160 offset:2592
	v_subrev_u32_e32 v161, s84, v248
	v_add3_u32 v158, s3, v224, v0
	s_waitcnt lgkmcnt(3)
	v_mfma_f32_32x32x16_bf16 v[50:65], v[178:181], v[102:105], v[230:245]
	s_waitcnt lgkmcnt(2)
	v_mfma_f32_32x32x16_bf16 v[34:49], v[182:185], v[102:105], v[230:245]
	s_waitcnt lgkmcnt(1)
	v_mfma_f32_32x32x16_bf16 v[50:65], v[186:189], v[98:101], v[50:65]
	s_waitcnt lgkmcnt(0)
	v_mfma_f32_32x32x16_bf16 v[34:49], v[190:193], v[98:101], v[34:49]
	ds_read2_b32 v[66:67], v161 offset0:63 offset1:62
	ds_read2_b32 v[68:69], v161 offset0:61 offset1:60
	ds_read2_b32 v[70:71], v161 offset0:59 offset1:58
	ds_read2_b32 v[72:73], v161 offset0:57 offset1:56
	ds_read2_b32 v[74:75], v161 offset0:47 offset1:46
	ds_read2_b32 v[76:77], v161 offset0:45 offset1:44
	ds_read2_b32 v[78:79], v161 offset0:43 offset1:42
	ds_read2_b32 v[80:81], v161 offset0:41 offset1:40
	s_nop 3
	s_waitcnt lgkmcnt(0)
	v_add_f32_e32 v50, v50, v66
	v_add_f32_e32 v51, v51, v67
	v_add_f32_e32 v52, v52, v68
	v_add_f32_e32 v53, v53, v69
	v_add_f32_e32 v54, v54, v70
	v_add_f32_e32 v55, v55, v71
	v_add_f32_e32 v56, v56, v72
	v_add_f32_e32 v57, v57, v73
	v_add_f32_e32 v58, v58, v74
	v_add_f32_e32 v59, v59, v75
	v_add_f32_e32 v60, v60, v76
	v_add_f32_e32 v61, v61, v77
	v_add_f32_e32 v62, v62, v78
	v_add_f32_e32 v63, v63, v79
	v_add_f32_e32 v64, v64, v80
	v_add_f32_e32 v65, v65, v81
	ds_read2_b32 v[82:83], v161 offset0:31 offset1:30
	ds_read2_b32 v[84:85], v161 offset0:29 offset1:28
	ds_read2_b32 v[86:87], v161 offset0:27 offset1:26
	ds_read2_b32 v[88:89], v161 offset0:25 offset1:24
	ds_read2_b32 v[90:91], v161 offset0:15 offset1:14
	ds_read2_b32 v[92:93], v161 offset0:13 offset1:12
	ds_read2_b32 v[94:95], v161 offset0:11 offset1:10
	ds_read2_b32 v[96:97], v161 offset0:9 offset1:8
	s_waitcnt lgkmcnt(0)
	v_add_f32_e32 v34, v34, v82
	v_add_f32_e32 v35, v35, v83
	v_add_f32_e32 v36, v36, v84
	v_add_f32_e32 v37, v37, v85
	v_add_f32_e32 v38, v38, v86
	v_add_f32_e32 v39, v39, v87
	v_add_f32_e32 v40, v40, v88
	v_add_f32_e32 v41, v41, v89
	v_add_f32_e32 v42, v42, v90
	v_add_f32_e32 v43, v43, v91
	v_add_f32_e32 v44, v44, v92
	v_add_f32_e32 v45, v45, v93
	v_add_f32_e32 v46, v46, v94
	v_add_f32_e32 v47, v47, v95
	v_add_f32_e32 v48, v48, v96
	v_add_f32_e32 v49, v49, v97
	ds_read_b128 v[146:149], v158 offset:20480
	ds_read_b128 v[142:145], v158 offset:20512
	ds_read_b128 v[150:153], v158 offset:25088
	ds_read_b128 v[138:141], v158 offset:25120
	ds_read_b128 v[134:137], v158 offset:20544
	ds_read_b128 v[126:129], v158 offset:20576
	ds_read_b128 v[130:133], v158 offset:25152
	ds_read_b128 v[122:125], v158 offset:25184
	v_max3_f32 v156, v50, v51, v52
	v_max3_f32 v156, v156, v53, v54
	v_max3_f32 v156, v156, v55, v56
	v_max3_f32 v156, v156, v57, v58
	v_max3_f32 v156, v156, v59, v60
	v_max3_f32 v156, v156, v61, v62
	v_max3_f32 v156, v156, v63, v64
	v_max3_f32 v156, v156, v65, v34
	v_max3_f32 v156, v156, v35, v36
	v_max3_f32 v156, v156, v37, v38
	v_max3_f32 v156, v156, v39, v40
	v_max3_f32 v156, v156, v41, v42
	v_max3_f32 v156, v156, v43, v44
	v_max3_f32 v156, v156, v45, v46
	v_max3_f32 v156, v156, v47, v48
	v_max_f32_e32 v156, v156, v49
	v_exp_f32_e32 v50, v50
	v_exp_f32_e32 v34, v34
	v_exp_f32_e32 v51, v51
	v_exp_f32_e32 v35, v35
	v_exp_f32_e32 v52, v52
	v_exp_f32_e32 v36, v36
	v_exp_f32_e32 v53, v53
	v_exp_f32_e32 v37, v37
	v_exp_f32_e32 v54, v54
	v_exp_f32_e32 v38, v38
	v_exp_f32_e32 v55, v55
	v_exp_f32_e32 v39, v39
	v_exp_f32_e32 v56, v56
	v_exp_f32_e32 v40, v40
	v_exp_f32_e32 v57, v57
	v_exp_f32_e32 v41, v41
	v_exp_f32_e32 v58, v58
	v_exp_f32_e32 v42, v42
	v_exp_f32_e32 v59, v59
	v_exp_f32_e32 v43, v43
	v_exp_f32_e32 v60, v60
	v_exp_f32_e32 v44, v44
	v_exp_f32_e32 v61, v61
	v_exp_f32_e32 v45, v45
	v_exp_f32_e32 v62, v62
	v_exp_f32_e32 v46, v46
	v_exp_f32_e32 v63, v63
	v_exp_f32_e32 v47, v47
	v_exp_f32_e32 v64, v64
	v_exp_f32_e32 v48, v48
	v_exp_f32_e32 v65, v65
	v_exp_f32_e32 v49, v49
	v_add_f32_e32 v160, v176, v156
	v_add_f32_e32 v161, v177, v157
	v_cmp_neq_f32_e64 s[4:5], v177, v176
	v_cmp_gt_f32_e32 vcc, v160, v161
	s_or_b64 vcc, s[4:5], vcc
	s_cbranch_vccnz .Ldn_slow_a
; __device__ __forceinline__ unsigned cvt_pk_bf16(float lo, float hi) { const f32x2 v = {lo, hi}; return __builtin_bit_cast(unsigned, __builtin_convertvector(v, bf16v2)); }
; __device__ __forceinline__ void softmax_tile(f32x16& s0, f32x16& s1, SM& st, float boff, ldsp_t vb, int hh, int r) {
;     ...
;   float ls = 0.f;
; #pragma unroll
;   for (int i = 0; i < 16; ++i) ls += s0[i] + s1[i];
;   st.l += ls;
;   bf16x8 pf[2][2];
; #pragma unroll
;   for (int s2 = 0; s2 < 2; ++s2) {
;     u32x4 w0, w1;
;     w0.x = cvt_pk_bf16(s0[8 * s2 + 0], s0[8 * s2 + 1]); w0.y = cvt_pk_bf16(s0[8 * s2 + 2], s0[8 * s2 + 3]); w0.z = cvt_pk_bf16(s0[8 * s2 + 4], s0[8 * s2 + 5]); w0.w = cvt_pk_bf16(s0[8 * s2 + 6], s0[8 * s2 + 7]);
;     w1.x = cvt_pk_bf16(s1[8 * s2 + 0], s1[8 * s2 + 1]); w1.y = cvt_pk_bf16(s1[8 * s2 + 2], s1[8 * s2 + 3]); w1.z = cvt_pk_bf16(s1[8 * s2 + 4], s1[8 * s2 + 5]); w1.w = cvt_pk_bf16(s1[8 * s2 + 6], s1[8 * s2 + 7]);
;     pf[0][s2] = __builtin_bit_cast(bf16x8, w0); pf[1][s2] = __builtin_bit_cast(bf16x8, w1);
;   }
; #pragma unroll
;   for (int kb = 0; kb < 2; ++kb)
; #pragma unroll
;     for (int s2 = 0; s2 < 2; ++s2) {
;       st.o0 = __builtin_amdgcn_mfma_f32_32x32x16_bf16(va0[kb][s2], pf[kb][s2], st.o0, 0, 0, 0);
;       st.o1 = __builtin_amdgcn_mfma_f32_32x32x16_bf16(va1[kb][s2], pf[kb][s2], st.o1, 0, 0, 0);
;     }
; template <int MODE, bool lookup, int MK>
; __device__ __forceinline__ void softmax_pv(f32x16& s0, f32x16& s1, SM& st, float boff, ldsp_t vb, LAS const float* tab, int t, int e_q, int posq, int hh, int r, bool mask_rt, float negv) {
;     ...
;       for (int i = 0; i < 16; ++i) { const int ek = ekb + (i & 7) + 16 * (i >> 3); int n0 = posq - (ek - koff), n1 = n0 - 32; n0 = (int)min((unsigned)n0, 128u); n1 = (int)min((unsigned)n1, 128u); s0[i] += tab[n0]; s1[i] += tab[n1]; }
;     }
;   }
;   if (need_mask) {
; #pragma unroll
;     for (int i = 0; i < 16; ++i) { const int ek0 = ekb + (i & 7) + 16 * (i >> 3), ek1 = ek0 + 32;
;       const bool v0 = (ek0 <= e_q) && (ek0 < klim) && (MODE != 2 || t == 0 || (e_q - ek0 < 128));
;       const bool v1 = (ek1 <= e_q) && (ek1 < klim) && (MODE != 2 || t == 0 || (e_q - ek1 < 128));
;       s0[i] = v0 ? s0[i] : negv; s1[i] = v1 ? s1[i] : negv; }
.Ldn_back_a:
	v_add_f32_e32 v250, v50, v34
	v_add_f32_e32 v249, 0, v250
	v_add_f32_e32 v250, v51, v35
	v_add_f32_e32 v249, v250, v249
	v_add_f32_e32 v250, v52, v36
	v_add_f32_e32 v249, v250, v249
	v_add_f32_e32 v250, v53, v37
	v_add_f32_e32 v249, v250, v249
	v_add_f32_e32 v250, v54, v38
	v_add_f32_e32 v249, v250, v249
	v_add_f32_e32 v250, v55, v39
	v_add_f32_e32 v249, v250, v249
	v_add_f32_e32 v250, v56, v40
	v_add_f32_e32 v249, v250, v249
	v_add_f32_e32 v250, v57, v41
	v_add_f32_e32 v249, v250, v249
	v_cvt_pk_bf16_f32 v50, v50, v51
	v_cvt_pk_bf16_f32 v51, v52, v53
	v_cvt_pk_bf16_f32 v52, v54, v55
	v_cvt_pk_bf16_f32 v53, v56, v57
	s_nop 0
	s_waitcnt lgkmcnt(7)
	v_mfma_f32_32x32x16_bf16 v[18:33], v[146:149], v[50:53], v[18:33]
	s_waitcnt lgkmcnt(5)
	v_mfma_f32_32x32x16_bf16 v[2:17], v[150:153], v[50:53], v[2:17]
	v_add_f32_e32 v250, v58, v42
	v_add_f32_e32 v249, v250, v249
	v_add_f32_e32 v250, v59, v43
	v_add_f32_e32 v249, v250, v249
	v_add_f32_e32 v250, v60, v44
	v_add_f32_e32 v249, v250, v249
	v_add_f32_e32 v250, v61, v45
	v_add_f32_e32 v249, v250, v249
	v_add_f32_e32 v250, v62, v46
	v_add_f32_e32 v249, v250, v249
	v_add_f32_e32 v250, v63, v47
	v_add_f32_e32 v249, v250, v249
	v_add_f32_e32 v250, v64, v48
	v_add_f32_e32 v249, v250, v249
	v_add_f32_e32 v250, v65, v49
	v_add_f32_e32 v249, v250, v249
	v_cvt_pk_bf16_f32 v58, v58, v59
	v_cvt_pk_bf16_f32 v59, v60, v61
	v_cvt_pk_bf16_f32 v60, v62, v63
	v_cvt_pk_bf16_f32 v61, v64, v65
	s_nop 0
	s_waitcnt lgkmcnt(6)
	v_mfma_f32_32x32x16_bf16 v[18:33], v[142:145], v[58:61], v[18:33]
	s_waitcnt lgkmcnt(4)
	v_mfma_f32_32x32x16_bf16 v[2:17], v[138:141], v[58:61], v[2:17]
	v_cvt_pk_bf16_f32 v34, v34, v35
	v_cvt_pk_bf16_f32 v35, v36, v37
	v_cvt_pk_bf16_f32 v36, v38, v39
	v_cvt_pk_bf16_f32 v37, v40, v41
	s_nop 0
	s_waitcnt lgkmcnt(3)
	v_mfma_f32_32x32x16_bf16 v[18:33], v[134:137], v[34:37], v[18:33]
	s_waitcnt lgkmcnt(1)
	v_mfma_f32_32x32x16_bf16 v[2:17], v[130:133], v[34:37], v[2:17]
	v_cvt_pk_bf16_f32 v42, v42, v43
	v_cvt_pk_bf16_f32 v43, v44, v45
	v_cvt_pk_bf16_f32 v44, v46, v47
	v_cvt_pk_bf16_f32 v45, v48, v49
	s_nop 0
	s_waitcnt lgkmcnt(2)
	v_mfma_f32_32x32x16_bf16 v[18:33], v[126:129], v[42:45], v[18:33]
	s_waitcnt lgkmcnt(0)
	v_mfma_f32_32x32x16_bf16 v[2:17], v[122:125], v[42:45], v[2:17]
	v_add_f32_e32 v228, v228, v249
	s_addk_i32 s84, 0x100
	v_add_u32_e32 v160, s2, v227
	ds_read_b128 v[194:197], v160
	ds_read_b128 v[198:201], v160 offset:2560
	ds_read_b128 v[202:205], v160 offset:32
	ds_read_b128 v[206:209], v160 offset:2592
	v_subrev_u32_e32 v161, s84, v248
	v_add3_u32 v158, s7, v224, v0
	s_waitcnt lgkmcnt(3)
	v_mfma_f32_32x32x16_bf16 v[82:97], v[194:197], v[102:105], v[230:245]
	s_waitcnt lgkmcnt(2)
	v_mfma_f32_32x32x16_bf16 v[66:81], v[198:201], v[102:105], v[230:245]
	s_waitcnt lgkmcnt(1)
	v_mfma_f32_32x32x16_bf16 v[82:97], v[202:205], v[98:101], v[82:97]
	s_waitcnt lgkmcnt(0)
	v_mfma_f32_32x32x16_bf16 v[66:81], v[206:209], v[98:101], v[66:81]
	ds_read2_b32 v[34:35], v161 offset0:63 offset1:62
	ds_read2_b32 v[36:37], v161 offset0:61 offset1:60
	ds_read2_b32 v[38:39], v161 offset0:59 offset1:58
	ds_read2_b32 v[40:41], v161 offset0:57 offset1:56
	ds_read2_b32 v[42:43], v161 offset0:47 offset1:46
	ds_read2_b32 v[44:45], v161 offset0:45 offset1:44
	ds_read2_b32 v[46:47], v161 offset0:43 offset1:42
	ds_read2_b32 v[48:49], v161 offset0:41 offset1:40
	s_nop 3
	s_waitcnt lgkmcnt(0)
	v_add_f32_e32 v82, v82, v34
	v_add_f32_e32 v83, v83, v35
	v_add_f32_e32 v84, v84, v36
	v_add_f32_e32 v85, v85, v37
	v_add_f32_e32 v86, v86, v38
	v_add_f32_e32 v87, v87, v39
	v_add_f32_e32 v88, v88, v40
	v_add_f32_e32 v89, v89, v41
	v_add_f32_e32 v90, v90, v42
	v_add_f32_e32 v91, v91, v43
	v_add_f32_e32 v92, v92, v44
	v_add_f32_e32 v93, v93, v45
	v_add_f32_e32 v94, v94, v46
	v_add_f32_e32 v95, v95, v47
	v_add_f32_e32 v96, v96, v48
	v_add_f32_e32 v97, v97, v49
	ds_read2_b32 v[50:51], v161 offset0:31 offset1:30
	ds_read2_b32 v[52:53], v161 offset0:29 offset1:28
	ds_read2_b32 v[54:55], v161 offset0:27 offset1:26
	ds_read2_b32 v[56:57], v161 offset0:25 offset1:24
	ds_read2_b32 v[58:59], v161 offset0:15 offset1:14
	ds_read2_b32 v[60:61], v161 offset0:13 offset1:12
	ds_read2_b32 v[62:63], v161 offset0:11 offset1:10
	ds_read2_b32 v[64:65], v161 offset0:9 offset1:8
	s_waitcnt lgkmcnt(0)
	v_add_f32_e32 v66, v66, v50
	v_add_f32_e32 v67, v67, v51
	v_add_f32_e32 v68, v68, v52
	v_add_f32_e32 v69, v69, v53
	v_add_f32_e32 v70, v70, v54
	v_add_f32_e32 v71, v71, v55
	v_add_f32_e32 v72, v72, v56
	v_add_f32_e32 v73, v73, v57
	v_add_f32_e32 v74, v74, v58
	v_add_f32_e32 v75, v75, v59
	v_add_f32_e32 v76, v76, v60
	v_add_f32_e32 v77, v77, v61
	v_add_f32_e32 v78, v78, v62
	v_add_f32_e32 v79, v79, v63
	v_add_f32_e32 v80, v80, v64
	v_add_f32_e32 v81, v81, v65
	ds_read_b128 v[178:181], v158 offset:20480
	ds_read_b128 v[182:185], v158 offset:20512
	ds_read_b128 v[186:189], v158 offset:25088
	ds_read_b128 v[190:193], v158 offset:25120
	ds_read_b128 v[194:197], v158 offset:20544
	ds_read_b128 v[198:201], v158 offset:20576
	ds_read_b128 v[202:205], v158 offset:25152
	ds_read_b128 v[206:209], v158 offset:25184
	v_max3_f32 v247, v82, v83, v84
	v_max3_f32 v247, v247, v85, v86
	v_max3_f32 v247, v247, v87, v88
	v_max3_f32 v247, v247, v89, v90
	v_max3_f32 v247, v247, v91, v92
	v_max3_f32 v247, v247, v93, v94
	v_max3_f32 v247, v247, v95, v96
	v_max3_f32 v247, v247, v97, v66
	v_max3_f32 v247, v247, v67, v68
	v_max3_f32 v247, v247, v69, v70
	v_max3_f32 v247, v247, v71, v72
	v_max3_f32 v247, v247, v73, v74
	v_max3_f32 v247, v247, v75, v76
	v_max3_f32 v247, v247, v77, v78
	v_max3_f32 v247, v247, v79, v80
	v_max_f32_e32 v247, v247, v81
	v_exp_f32_e32 v82, v82
	v_exp_f32_e32 v66, v66
	v_exp_f32_e32 v83, v83
	v_exp_f32_e32 v67, v67
	v_exp_f32_e32 v84, v84
	v_exp_f32_e32 v68, v68
	v_exp_f32_e32 v85, v85
	v_exp_f32_e32 v69, v69
	v_exp_f32_e32 v86, v86
	v_exp_f32_e32 v70, v70
	v_exp_f32_e32 v87, v87
	v_exp_f32_e32 v71, v71
	v_exp_f32_e32 v88, v88
	v_exp_f32_e32 v72, v72
	v_exp_f32_e32 v89, v89
	v_exp_f32_e32 v73, v73
	v_exp_f32_e32 v90, v90
	v_exp_f32_e32 v74, v74
	v_exp_f32_e32 v91, v91
	v_exp_f32_e32 v75, v75
	v_exp_f32_e32 v92, v92
	v_exp_f32_e32 v76, v76
	v_exp_f32_e32 v93, v93
	v_exp_f32_e32 v77, v77
	v_exp_f32_e32 v94, v94
	v_exp_f32_e32 v78, v78
	v_exp_f32_e32 v95, v95
	v_exp_f32_e32 v79, v79
	v_exp_f32_e32 v96, v96
	v_exp_f32_e32 v80, v80
	v_exp_f32_e32 v97, v97
	v_exp_f32_e32 v81, v81
	v_add_f32_e32 v160, v176, v247
	v_add_f32_e32 v161, v177, v157
	v_cmp_neq_f32_e64 s[4:5], v177, v176
	v_cmp_gt_f32_e32 vcc, v160, v161
	s_or_b64 vcc, s[4:5], vcc
	s_cbranch_vccnz .Ldn_slow_b
; #define LAS __attribute__((address_space(3)))
; __device__ __forceinline__ unsigned cvt_pk_bf16(float lo, float hi) { const f32x2 v = {lo, hi}; return __builtin_bit_cast(unsigned, __builtin_convertvector(v, bf16v2)); }
; __device__ __forceinline__ void softmax_tile(f32x16& s0, f32x16& s1, SM& st, float boff, ldsp_t vb, int hh, int r) {
;     ...
;   float ls = 0.f;
; #pragma unroll
;   for (int i = 0; i < 16; ++i) ls += s0[i] + s1[i];
;   st.l += ls;
;   bf16x8 pf[2][2];
; #pragma unroll
;   for (int s2 = 0; s2 < 2; ++s2) {
;     u32x4 w0, w1;
;     w0.x = cvt_pk_bf16(s0[8 * s2 + 0], s0[8 * s2 + 1]); w0.y = cvt_pk_bf16(s0[8 * s2 + 2], s0[8 * s2 + 3]); w0.z = cvt_pk_bf16(s0[8 * s2 + 4], s0[8 * s2 + 5]); w0.w = cvt_pk_bf16(s0[8 * s2 + 6], s0[8 * s2 + 7]);
;     w1.x = cvt_pk_bf16(s1[8 * s2 + 0], s1[8 * s2 + 1]); w1.y = cvt_pk_bf16(s1[8 * s2 + 2], s1[8 * s2 + 3]); w1.z = cvt_pk_bf16(s1[8 * s2 + 4], s1[8 * s2 + 5]); w1.w = cvt_pk_bf16(s1[8 * s2 + 6], s1[8 * s2 + 7]);
;     pf[0][s2] = __builtin_bit_cast(bf16x8, w0); pf[1][s2] = __builtin_bit_cast(bf16x8, w1);
;   }
; #pragma unroll
;   for (int kb = 0; kb < 2; ++kb)
; #pragma unroll
;     for (int s2 = 0; s2 < 2; ++s2) {
;       st.o0 = __builtin_amdgcn_mfma_f32_32x32x16_bf16(va0[kb][s2], pf[kb][s2], st.o0, 0, 0, 0);
;       st.o1 = __builtin_amdgcn_mfma_f32_32x32x16_bf16(va1[kb][s2], pf[kb][s2], st.o1, 0, 0, 0);
;     }
; template <int MODE>
; __device__ __forceinline__ void attn_item(const Params& P, int layer, int b, int h, int map, int qb) {
;     ...
;   auto issue = [&](Stage& st, int t) {
; #pragma unroll
;     for (int u = 0; u < NLK; ++u) { int c = tid + 512 * u; if (c >= NKC) c -= (NKC % 512 == 0 ? 512 : NKC % 512);
;       const int row = c / CPR, cc = c % CPR; st.k[u] = *(const u32x4*)(kp + (size_t)(64 * t + row) * KLD + cc * 8); }
;     { const int row = tid >> 3, cc = tid & 7; st.v = *(const u32x4*)(vp + (size_t)row * E + 64 * t + cc * 8); }
;   };
;   auto commit = [&](const Stage& st, int bufi) {
; #pragma unroll
;     for (int u = 0; u < NLK; ++u) { int c = tid + 512 * u; if (c >= NKC) c -= (NKC % 512 == 0 ? 512 : NKC % 512);
;       const int row = c / CPR, cc = c % CPR; *(LAS u32x4*)(lds + bufi * KBUF + row * KSTR + cc * 16) = st.k[u]; }
;     { const int row = tid >> 3, cc = tid & 7; *(LAS u32x4*)(lds + 4 * KBUF + bufi * VBUF + row * 144 + cc * 16) = st.v; }
;   };
.Ldn_back_b:
	v_add_f32_e32 v250, v82, v66
	v_add_f32_e32 v249, 0, v250
	v_add_f32_e32 v250, v83, v67
	v_add_f32_e32 v249, v250, v249
	v_add_f32_e32 v250, v84, v68
	v_add_f32_e32 v249, v250, v249
	v_add_f32_e32 v250, v85, v69
	v_add_f32_e32 v249, v250, v249
	v_add_f32_e32 v250, v86, v70
	v_add_f32_e32 v249, v250, v249
	v_add_f32_e32 v250, v87, v71
	v_add_f32_e32 v249, v250, v249
	v_add_f32_e32 v250, v88, v72
	v_add_f32_e32 v249, v250, v249
	v_add_f32_e32 v250, v89, v73
	v_add_f32_e32 v249, v250, v249
	v_cvt_pk_bf16_f32 v82, v82, v83
	v_cvt_pk_bf16_f32 v83, v84, v85
	v_cvt_pk_bf16_f32 v84, v86, v87
	v_cvt_pk_bf16_f32 v85, v88, v89
	s_nop 0
	s_waitcnt lgkmcnt(7)
	v_mfma_f32_32x32x16_bf16 v[18:33], v[178:181], v[82:85], v[18:33]
	s_waitcnt lgkmcnt(5)
	v_mfma_f32_32x32x16_bf16 v[2:17], v[186:189], v[82:85], v[2:17]
	v_add_f32_e32 v250, v90, v74
	v_add_f32_e32 v249, v250, v249
	v_add_f32_e32 v250, v91, v75
	v_add_f32_e32 v249, v250, v249
	v_add_f32_e32 v250, v92, v76
	v_add_f32_e32 v249, v250, v249
	v_add_f32_e32 v250, v93, v77
	v_add_f32_e32 v249, v250, v249
	v_add_f32_e32 v250, v94, v78
	v_add_f32_e32 v249, v250, v249
	v_add_f32_e32 v250, v95, v79
	v_add_f32_e32 v249, v250, v249
	v_add_f32_e32 v250, v96, v80
	v_add_f32_e32 v249, v250, v249
	v_add_f32_e32 v250, v97, v81
	v_add_f32_e32 v249, v250, v249
	v_cvt_pk_bf16_f32 v90, v90, v91
	v_cvt_pk_bf16_f32 v91, v92, v93
	v_cvt_pk_bf16_f32 v92, v94, v95
	v_cvt_pk_bf16_f32 v93, v96, v97
	s_nop 0
	s_waitcnt lgkmcnt(6)
	v_mfma_f32_32x32x16_bf16 v[18:33], v[182:185], v[90:93], v[18:33]
	s_waitcnt lgkmcnt(4)
	v_mfma_f32_32x32x16_bf16 v[2:17], v[190:193], v[90:93], v[2:17]
	v_cvt_pk_bf16_f32 v66, v66, v67
	v_cvt_pk_bf16_f32 v67, v68, v69
	v_cvt_pk_bf16_f32 v68, v70, v71
	v_cvt_pk_bf16_f32 v69, v72, v73
	s_nop 0
	s_waitcnt lgkmcnt(3)
	v_mfma_f32_32x32x16_bf16 v[18:33], v[194:197], v[66:69], v[18:33]
	s_waitcnt lgkmcnt(1)
	v_mfma_f32_32x32x16_bf16 v[2:17], v[202:205], v[66:69], v[2:17]
	v_cvt_pk_bf16_f32 v74, v74, v75
	v_cvt_pk_bf16_f32 v75, v76, v77
	v_cvt_pk_bf16_f32 v76, v78, v79
	v_cvt_pk_bf16_f32 v77, v80, v81
	s_nop 0
	s_waitcnt lgkmcnt(2)
	v_mfma_f32_32x32x16_bf16 v[18:33], v[198:201], v[74:77], v[18:33]
	s_waitcnt lgkmcnt(0)
	v_mfma_f32_32x32x16_bf16 v[2:17], v[206:209], v[74:77], v[2:17]
	v_add_f32_e32 v228, v228, v249
	s_xor_b32 s2, s78, 2
	s_mul_i32 s3, s2, 0x1400
	v_add_u32_e32 v160, s3, v171
	s_mulk_i32 s2, 0x2400
	s_waitcnt vmcnt(3)
	ds_write_b128 v160, v[106:109]
	v_add_u32_e32 v160, s2, v222
	s_add_i32 s2, s48, 4
	s_min_i32 s2, s2, s63
	s_lshl_b32 s90, s2, 6
	s_waitcnt vmcnt(2)
	ds_write_b128 v160, v[110:113] offset:20480
	v_add_u32_e32 v160, s90, v170
	v_ashrrev_i32_e32 v161, 31, v160
	v_lshlrev_b64 v[160:161], 7, v[160:161]
	v_lshl_add_u64 v[160:161], v[174:175], 0, v[160:161]
	v_lshl_add_u64 v[250:251], s[90:91], 1, v[172:173]
	global_load_dwordx4 v[106:109], v[160:161], off
	global_load_dwordx4 v[110:113], v[250:251], off
	s_xor_b32 s2, s78, 3
	s_mul_i32 s3, s2, 0x1400
	v_add_u32_e32 v160, s3, v171
	s_mulk_i32 s2, 0x2400
	s_waitcnt vmcnt(3)
	ds_write_b128 v160, v[114:117]
	v_add_u32_e32 v160, s2, v222
	s_add_i32 s2, s48, 5
	s_min_i32 s2, s2, s63
	s_lshl_b32 s90, s2, 6
	s_waitcnt vmcnt(2)
	ds_write_b128 v160, v[118:121] offset:20480
	v_add_u32_e32 v160, s90, v170
	v_ashrrev_i32_e32 v161, 31, v160
	v_lshlrev_b64 v[160:161], 7, v[160:161]
	v_lshl_add_u64 v[160:161], v[174:175], 0, v[160:161]
	v_lshl_add_u64 v[250:251], s[90:91], 1, v[172:173]
	global_load_dwordx4 v[114:117], v[160:161], off
	global_load_dwordx4 v[118:121], v[250:251], off
	s_add_i32 s48, s48, 2
	s_cmp_gt_u32 s48, s62
	s_waitcnt lgkmcnt(0)
	s_barrier
	s_cbranch_scc1 .LBB0_1288
	s_branch .LBB0_1251
; __device__ __forceinline__ float max32(float v) { return __builtin_fmaxf(v, xhalf(v)); }
; __device__ __forceinline__ void softmax_tile(f32x16& s0, f32x16& s1, SM& st, float boff, ldsp_t vb, int hh, int r) {
;     ...
;   if (__any((zmax + boff > st.m + DEFER_THR) || (st.m != boff))) {
;     const float zt = max32(zmax) + boff; const bool need = zt > st.m + DEFER_THR;
;     const float mn = need ? zt : st.m, alpha = __builtin_amdgcn_exp2f(st.m - mn), f = __builtin_amdgcn_exp2f(__builtin_fminf(boff - mn, 120.f)); st.m = mn;
; #pragma unroll
;     for (int i = 0; i < 16; ++i) { s0[i] *= f; s1[i] *= f; st.o0[i] *= alpha; st.o1[i] *= alpha; }
;     st.l *= alpha;
.Ldn_slow_a:
	s_nop 15
	v_lshlrev_b32_e32 v160, 2, v210
	v_xor_b32_e32 v160, 0x80, v160
	v_max_f32_e32 v161, v156, v156
	ds_bpermute_b32 v160, v160, v156
	s_waitcnt lgkmcnt(0)
	v_max_f32_e32 v160, v160, v160
	v_max_f32_e32 v160, v161, v160
	v_add_f32_e32 v160, v176, v160
	v_add_f32_e32 v161, v177, v157
	v_cmp_gt_f32_e32 vcc, v160, v161
	s_nop 1
	v_cndmask_b32_e32 v251, v177, v160, vcc
	v_sub_f32_e32 v160, v176, v251
	v_min_f32_e32 v160, 0x42f00000, v160
	v_sub_f32_e32 v161, v177, v251
	v_exp_f32_e32 v160, v160
	v_exp_f32_e32 v161, v161
	v_mov_b32_e32 v177, v251
	s_nop 0
	v_mul_f32_e32 v50, v50, v160
	v_mul_f32_e32 v34, v34, v160
	v_mul_f32_e32 v51, v51, v160
	v_mul_f32_e32 v35, v35, v160
	v_mul_f32_e32 v52, v52, v160
	v_mul_f32_e32 v36, v36, v160
	v_mul_f32_e32 v53, v53, v160
	v_mul_f32_e32 v37, v37, v160
	v_mul_f32_e32 v54, v54, v160
	v_mul_f32_e32 v38, v38, v160
	v_mul_f32_e32 v55, v55, v160
	v_mul_f32_e32 v39, v39, v160
	v_mul_f32_e32 v56, v56, v160
	v_mul_f32_e32 v40, v40, v160
	v_mul_f32_e32 v57, v57, v160
	v_mul_f32_e32 v41, v41, v160
	v_mul_f32_e32 v58, v58, v160
	v_mul_f32_e32 v42, v42, v160
	v_mul_f32_e32 v59, v59, v160
	v_mul_f32_e32 v43, v43, v160
	v_mul_f32_e32 v60, v60, v160
	v_mul_f32_e32 v44, v44, v160
	v_mul_f32_e32 v61, v61, v160
	v_mul_f32_e32 v45, v45, v160
	v_mul_f32_e32 v62, v62, v160
	v_mul_f32_e32 v46, v46, v160
	v_mul_f32_e32 v63, v63, v160
	v_mul_f32_e32 v47, v47, v160
	v_mul_f32_e32 v64, v64, v160
	v_mul_f32_e32 v48, v48, v160
	v_mul_f32_e32 v65, v65, v160
	v_mul_f32_e32 v49, v49, v160
	v_mul_f32_e32 v2, v2, v161
	v_mul_f32_e32 v3, v3, v161
	v_mul_f32_e32 v4, v4, v161
	v_mul_f32_e32 v5, v5, v161
	v_mul_f32_e32 v6, v6, v161
	v_mul_f32_e32 v7, v7, v161
	v_mul_f32_e32 v8, v8, v161
	v_mul_f32_e32 v9, v9, v161
	v_mul_f32_e32 v10, v10, v161
	v_mul_f32_e32 v11, v11, v161
	v_mul_f32_e32 v12, v12, v161
	v_mul_f32_e32 v13, v13, v161
	v_mul_f32_e32 v14, v14, v161
	v_mul_f32_e32 v15, v15, v161
	v_mul_f32_e32 v16, v16, v161
	v_mul_f32_e32 v17, v17, v161
	v_mul_f32_e32 v18, v18, v161
	v_mul_f32_e32 v19, v19, v161
	v_mul_f32_e32 v20, v20, v161
	v_mul_f32_e32 v21, v21, v161
	v_mul_f32_e32 v22, v22, v161
	v_mul_f32_e32 v23, v23, v161
	v_mul_f32_e32 v24, v24, v161
	v_mul_f32_e32 v25, v25, v161
	v_mul_f32_e32 v26, v26, v161
	v_mul_f32_e32 v27, v27, v161
	v_mul_f32_e32 v28, v28, v161
	v_mul_f32_e32 v29, v29, v161
	v_mul_f32_e32 v30, v30, v161
	v_mul_f32_e32 v31, v31, v161
	v_mul_f32_e32 v32, v32, v161
	v_mul_f32_e32 v33, v33, v161
	v_mul_f32_e32 v228, v228, v161
	s_branch .Ldn_back_a
.Ldn_slow_b:
	s_nop 15
	v_lshlrev_b32_e32 v160, 2, v210
	v_xor_b32_e32 v160, 0x80, v160
	v_max_f32_e32 v161, v247, v247
	ds_bpermute_b32 v160, v160, v247
	s_waitcnt lgkmcnt(0)
	v_max_f32_e32 v160, v160, v160
	v_max_f32_e32 v160, v161, v160
	v_add_f32_e32 v160, v176, v160
	v_add_f32_e32 v161, v177, v157
	v_cmp_gt_f32_e32 vcc, v160, v161
	s_nop 1
	v_cndmask_b32_e32 v251, v177, v160, vcc
	v_sub_f32_e32 v160, v176, v251
	v_min_f32_e32 v160, 0x42f00000, v160
	v_sub_f32_e32 v161, v177, v251
	v_exp_f32_e32 v160, v160
	v_exp_f32_e32 v161, v161
	v_mov_b32_e32 v177, v251
	s_nop 0
	v_mul_f32_e32 v82, v82, v160
	v_mul_f32_e32 v66, v66, v160
	v_mul_f32_e32 v83, v83, v160
	v_mul_f32_e32 v67, v67, v160
	v_mul_f32_e32 v84, v84, v160
	v_mul_f32_e32 v68, v68, v160
	v_mul_f32_e32 v85, v85, v160
	v_mul_f32_e32 v69, v69, v160
	v_mul_f32_e32 v86, v86, v160
	v_mul_f32_e32 v70, v70, v160
	v_mul_f32_e32 v87, v87, v160
	v_mul_f32_e32 v71, v71, v160
	v_mul_f32_e32 v88, v88, v160
	v_mul_f32_e32 v72, v72, v160
	v_mul_f32_e32 v89, v89, v160
	v_mul_f32_e32 v73, v73, v160
	v_mul_f32_e32 v90, v90, v160
	v_mul_f32_e32 v74, v74, v160
	v_mul_f32_e32 v91, v91, v160
	v_mul_f32_e32 v75, v75, v160
	v_mul_f32_e32 v92, v92, v160
	v_mul_f32_e32 v76, v76, v160
	v_mul_f32_e32 v93, v93, v160
	v_mul_f32_e32 v77, v77, v160
	v_mul_f32_e32 v94, v94, v160
	v_mul_f32_e32 v78, v78, v160
	v_mul_f32_e32 v95, v95, v160
	v_mul_f32_e32 v79, v79, v160
	v_mul_f32_e32 v96, v96, v160
	v_mul_f32_e32 v80, v80, v160
	v_mul_f32_e32 v97, v97, v160
	v_mul_f32_e32 v81, v81, v160
	v_mul_f32_e32 v2, v2, v161
	v_mul_f32_e32 v3, v3, v161
	v_mul_f32_e32 v4, v4, v161
	v_mul_f32_e32 v5, v5, v161
	v_mul_f32_e32 v6, v6, v161
	v_mul_f32_e32 v7, v7, v161
	v_mul_f32_e32 v8, v8, v161
	v_mul_f32_e32 v9, v9, v161
	v_mul_f32_e32 v10, v10, v161
	v_mul_f32_e32 v11, v11, v161
	v_mul_f32_e32 v12, v12, v161
	v_mul_f32_e32 v13, v13, v161
	v_mul_f32_e32 v14, v14, v161
	v_mul_f32_e32 v15, v15, v161
	v_mul_f32_e32 v16, v16, v161
	v_mul_f32_e32 v17, v17, v161
	v_mul_f32_e32 v18, v18, v161
	v_mul_f32_e32 v19, v19, v161
	v_mul_f32_e32 v20, v20, v161
	v_mul_f32_e32 v21, v21, v161
	v_mul_f32_e32 v22, v22, v161
	v_mul_f32_e32 v23, v23, v161
	v_mul_f32_e32 v24, v24, v161
	v_mul_f32_e32 v25, v25, v161
	v_mul_f32_e32 v26, v26, v161
	v_mul_f32_e32 v27, v27, v161
	v_mul_f32_e32 v28, v28, v161
	v_mul_f32_e32 v29, v29, v161
	v_mul_f32_e32 v30, v30, v161
	v_mul_f32_e32 v31, v31, v161
	v_mul_f32_e32 v32, v32, v161
	v_mul_f32_e32 v33, v33, v161
	v_mul_f32_e32 v228, v228, v161
	s_branch .Ldn_back_b
